# in-projection GEMM epilogue: straight path for plain tiles (one base address, no per-piece flag tests) with write-through (sc1) stores like the up GEMM's
# speedup vs baseline: 1.1182x; 1.0057x over previous
.Lepip_end:
	s_cbranch_vccnz .LBB0_224
	s_andn2_b64 vcc, exec, s[2:3]
	s_cbranch_vccnz .LBB0_223
	s_barrier
	s_branch .LBB0_223
.Lepip_plain:
	v_lshl_add_u32 v130, s6, 8, v150
	v_mov_b64_e32 v[128:129], s[8:9]
	v_mad_i64_i32 v[128:129], s[24:25], v130, s88, v[128:129]
	v_lshl_add_u64 v[128:129], v[148:149], 1, v[128:129]
	v_cvt_pk_bf16_f32 v120, v120, v121
	v_cvt_pk_bf16_f32 v121, v122, v123
	v_cvt_pk_bf16_f32 v122, v124, v125
	v_cvt_pk_bf16_f32 v123, v126, v127
	flat_store_dwordx4 v[128:129], v[120:123] sc1
	v_cvt_pk_bf16_f32 v112, v112, v113
	v_cvt_pk_bf16_f32 v113, v114, v115
	v_cvt_pk_bf16_f32 v114, v116, v117
	v_cvt_pk_bf16_f32 v115, v118, v119
	flat_store_dwordx4 v[128:129], v[112:115] offset:256 sc1
	s_mov_b64 s[24:25], 0x14000
	v_lshl_add_u64 v[130:131], s[24:25], 0, v[128:129]
	v_cvt_pk_bf16_f32 v104, v104, v105
	v_cvt_pk_bf16_f32 v105, v106, v107
	v_cvt_pk_bf16_f32 v106, v108, v109
	v_cvt_pk_bf16_f32 v107, v110, v111
	flat_store_dwordx4 v[130:131], v[104:107] sc1
	v_cvt_pk_bf16_f32 v96, v96, v97
	v_cvt_pk_bf16_f32 v97, v98, v99
	v_cvt_pk_bf16_f32 v98, v100, v101
	v_cvt_pk_bf16_f32 v99, v102, v103
	flat_store_dwordx4 v[130:131], v[96:99] offset:256 sc1
	s_mov_b64 s[24:25], 0x28000
	v_lshl_add_u64 v[130:131], s[24:25], 0, v[128:129]
	v_cvt_pk_bf16_f32 v88, v88, v89
	v_cvt_pk_bf16_f32 v89, v90, v91
	v_cvt_pk_bf16_f32 v90, v92, v93
	v_cvt_pk_bf16_f32 v91, v94, v95
	flat_store_dwordx4 v[130:131], v[88:91] sc1
	v_cvt_pk_bf16_f32 v80, v80, v81
	v_cvt_pk_bf16_f32 v81, v82, v83
	v_cvt_pk_bf16_f32 v82, v84, v85
	v_cvt_pk_bf16_f32 v83, v86, v87
	flat_store_dwordx4 v[130:131], v[80:83] offset:256 sc1
	s_mov_b64 s[24:25], 0x3c000
	v_lshl_add_u64 v[130:131], s[24:25], 0, v[128:129]
	v_cvt_pk_bf16_f32 v72, v72, v73
	v_cvt_pk_bf16_f32 v73, v74, v75
	v_cvt_pk_bf16_f32 v74, v76, v77
	v_cvt_pk_bf16_f32 v75, v78, v79
	flat_store_dwordx4 v[130:131], v[72:75] sc1
	v_cvt_pk_bf16_f32 v64, v64, v65
	v_cvt_pk_bf16_f32 v65, v66, v67
	v_cvt_pk_bf16_f32 v66, v68, v69
	v_cvt_pk_bf16_f32 v67, v70, v71
	flat_store_dwordx4 v[130:131], v[64:67] offset:256 sc1
	s_mov_b64 s[24:25], 0xa0000
	v_lshl_add_u64 v[130:131], s[24:25], 0, v[128:129]
	v_cvt_pk_bf16_f32 v56, v56, v57
	v_cvt_pk_bf16_f32 v57, v58, v59
	v_cvt_pk_bf16_f32 v58, v60, v61
	v_cvt_pk_bf16_f32 v59, v62, v63
	flat_store_dwordx4 v[130:131], v[56:59] sc1
	v_cvt_pk_bf16_f32 v48, v48, v49
	v_cvt_pk_bf16_f32 v49, v50, v51
	v_cvt_pk_bf16_f32 v50, v52, v53
	v_cvt_pk_bf16_f32 v51, v54, v55
	flat_store_dwordx4 v[130:131], v[48:51] offset:256 sc1
	s_mov_b64 s[24:25], 0xb4000
	v_lshl_add_u64 v[130:131], s[24:25], 0, v[128:129]
	v_cvt_pk_bf16_f32 v40, v40, v41
	v_cvt_pk_bf16_f32 v41, v42, v43
	v_cvt_pk_bf16_f32 v42, v44, v45
	v_cvt_pk_bf16_f32 v43, v46, v47
	flat_store_dwordx4 v[130:131], v[40:43] sc1
	v_cvt_pk_bf16_f32 v32, v32, v33
	v_cvt_pk_bf16_f32 v33, v34, v35
	v_cvt_pk_bf16_f32 v34, v36, v37
	v_cvt_pk_bf16_f32 v35, v38, v39
	flat_store_dwordx4 v[130:131], v[32:35] offset:256 sc1
	s_mov_b64 s[24:25], 0xc8000
	v_lshl_add_u64 v[130:131], s[24:25], 0, v[128:129]
	v_cvt_pk_bf16_f32 v24, v24, v25
	v_cvt_pk_bf16_f32 v25, v26, v27
	v_cvt_pk_bf16_f32 v26, v28, v29
	v_cvt_pk_bf16_f32 v27, v30, v31
	flat_store_dwordx4 v[130:131], v[24:27] sc1
	v_cvt_pk_bf16_f32 v16, v16, v17
	v_cvt_pk_bf16_f32 v17, v18, v19
	v_cvt_pk_bf16_f32 v18, v20, v21
	v_cvt_pk_bf16_f32 v19, v22, v23
	flat_store_dwordx4 v[130:131], v[16:19] offset:256 sc1
	s_mov_b64 s[24:25], 0xdc000
	v_lshl_add_u64 v[130:131], s[24:25], 0, v[128:129]
	v_cvt_pk_bf16_f32 v8, v8, v9
	v_cvt_pk_bf16_f32 v9, v10, v11
	v_cvt_pk_bf16_f32 v10, v12, v13
	v_cvt_pk_bf16_f32 v11, v14, v15
	flat_store_dwordx4 v[130:131], v[8:11] sc1
	v_cvt_pk_bf16_f32 v0, v0, v1
	v_cvt_pk_bf16_f32 v1, v2, v3
	v_cvt_pk_bf16_f32 v2, v4, v5
	v_cvt_pk_bf16_f32 v3, v6, v7
	flat_store_dwordx4 v[130:131], v[0:3] offset:256 sc1
	s_andn2_b64 vcc, exec, s[4:5]
	s_mov_b64 s[0:1], -1
	s_branch .Lepip_end
